# previous + ada epilogue bias loaded once (20 serialized reloads removed)
# speedup vs baseline: 1.0760x; 1.0019x over previous
.LBB0_205:
	ds_read_b128 v[102:105], v108
	ds_read_b128 v[112:115], v108 offset:1024
	ds_read_b128 v[116:119], v108 offset:2048
	ds_read_b128 v[120:123], v108 offset:3072
	s_add_u32 s68, s52, 0xfff80080
	s_addc_u32 s69, s53, -1
	s_cmp_eq_u32 s93, 12
	s_cselect_b32 s71, s2, s69
	s_cselect_b32 s70, s17, s68
	s_cselect_b32 s69, s23, s31
	s_cselect_b32 s68, s25, s29
	v_lshl_add_u64 v[156:157], s[52:53], 0, v[98:99]
	s_add_i32 m0, s21, 0xc000
	ds_read_b128 v[124:127], v109
	ds_read_b128 v[128:131], v109 offset:1024
	ds_read_b128 v[132:135], v109 offset:2048
	ds_read_b128 v[136:139], v109 offset:3072
	ds_read_b128 v[140:143], v109 offset:4096
	ds_read_b128 v[144:147], v109 offset:5120
	ds_read_b128 v[148:151], v109 offset:6144
	ds_read_b128 v[152:155], v109 offset:7168
	global_load_lds_dwordx4 v[156:157], off
	v_lshl_add_u64 v[156:157], s[52:53], 0, v[100:101]
	s_add_i32 m0, s21, 0xe000
	s_nop 0
	global_load_lds_dwordx4 v[156:157], off
	s_waitcnt lgkmcnt(8)
	s_barrier
	s_waitcnt lgkmcnt(0)
	s_setprio 1
	s_waitcnt lgkmcnt(0)
	v_mfma_f32_16x16x32_bf16 v[80:83], v[102:105], v[124:127], v[80:83]
	v_mfma_f32_16x16x32_bf16 v[76:79], v[116:119], v[124:127], v[76:79]
	v_mfma_f32_16x16x32_bf16 v[64:67], v[102:105], v[132:135], v[64:67]
	v_mfma_f32_16x16x32_bf16 v[60:63], v[116:119], v[132:135], v[60:63]
	v_mfma_f32_16x16x32_bf16 v[48:51], v[102:105], v[140:143], v[48:51]
	v_mfma_f32_16x16x32_bf16 v[44:47], v[116:119], v[140:143], v[44:47]
	v_mfma_f32_16x16x32_bf16 v[30:33], v[102:105], v[148:151], v[30:33]
	v_mfma_f32_16x16x32_bf16 v[26:29], v[116:119], v[148:151], v[26:29]
	v_mfma_f32_16x16x32_bf16 v[80:83], v[112:115], v[128:131], v[80:83]
	v_mfma_f32_16x16x32_bf16 v[76:79], v[120:123], v[128:131], v[76:79]
	v_mfma_f32_16x16x32_bf16 v[64:67], v[112:115], v[136:139], v[64:67]
	v_mfma_f32_16x16x32_bf16 v[60:63], v[120:123], v[136:139], v[60:63]
	v_mfma_f32_16x16x32_bf16 v[48:51], v[112:115], v[144:147], v[48:51]
	v_mfma_f32_16x16x32_bf16 v[44:47], v[120:123], v[144:147], v[44:47]
	v_mfma_f32_16x16x32_bf16 v[30:33], v[112:115], v[152:155], v[30:33]
	v_mfma_f32_16x16x32_bf16 v[26:29], v[120:123], v[152:155], v[26:29]
	s_setprio 0
	s_barrier
	s_add_i32 s94, s91, s72
	v_lshl_add_u64 v[172:173], s[68:69], 0, v[84:85]
	s_mov_b32 m0, s94
	ds_read_b128 v[156:159], v110
	ds_read_b128 v[160:163], v110 offset:1024
	ds_read_b128 v[164:167], v110 offset:2048
	ds_read_b128 v[168:171], v110 offset:3072
	global_load_lds_dwordx4 v[172:173], off
	v_lshl_add_u64 v[174:175], s[68:69], 0, v[86:87]
	s_add_i32 m0, s94, 0x2000
	s_nop 0
	global_load_lds_dwordx4 v[174:175], off
	s_barrier
	s_waitcnt lgkmcnt(0)
	s_setprio 1
	s_waitcnt lgkmcnt(0)
	v_mfma_f32_16x16x32_bf16 v[72:75], v[156:159], v[124:127], v[72:75]
	v_mfma_f32_16x16x32_bf16 v[68:71], v[164:167], v[124:127], v[68:71]
	v_mfma_f32_16x16x32_bf16 v[56:59], v[156:159], v[132:135], v[56:59]
	v_mfma_f32_16x16x32_bf16 v[52:55], v[164:167], v[132:135], v[52:55]
	v_mfma_f32_16x16x32_bf16 v[40:43], v[156:159], v[140:143], v[40:43]
	v_mfma_f32_16x16x32_bf16 v[36:39], v[164:167], v[140:143], v[36:39]
	v_mfma_f32_16x16x32_bf16 v[22:25], v[156:159], v[148:151], v[22:25]
	v_mfma_f32_16x16x32_bf16 v[18:21], v[164:167], v[148:151], v[18:21]
	v_mfma_f32_16x16x32_bf16 v[72:75], v[160:163], v[128:131], v[72:75]
	v_mfma_f32_16x16x32_bf16 v[68:71], v[168:171], v[128:131], v[68:71]
	v_mfma_f32_16x16x32_bf16 v[56:59], v[160:163], v[136:139], v[56:59]
	v_mfma_f32_16x16x32_bf16 v[52:55], v[168:171], v[136:139], v[52:55]
	v_mfma_f32_16x16x32_bf16 v[40:43], v[160:163], v[144:147], v[40:43]
	v_mfma_f32_16x16x32_bf16 v[36:39], v[168:171], v[144:147], v[36:39]
	v_mfma_f32_16x16x32_bf16 v[22:25], v[160:163], v[152:155], v[22:25]
	v_mfma_f32_16x16x32_bf16 v[18:21], v[168:171], v[152:155], v[18:21]
	s_setprio 0
	s_mov_b32 m0, s21
	v_lshl_add_u64 v[176:177], s[70:71], 0, v[84:85]
	s_barrier
	ds_read_b128 v[124:127], v109 offset:16384
	ds_read_b128 v[128:131], v109 offset:17408
	global_load_lds_dwordx4 v[176:177], off
	v_lshl_add_u64 v[178:179], s[70:71], 0, v[86:87]
	s_mov_b32 m0, s73
	s_nop 0
	global_load_lds_dwordx4 v[178:179], off
	s_barrier
	s_waitcnt lgkmcnt(0)
	s_setprio 1
	s_waitcnt lgkmcnt(0)
	v_mfma_f32_16x16x32_bf16 v[14:17], v[102:105], v[124:127], v[14:17]
	v_mfma_f32_16x16x32_bf16 v[10:13], v[116:119], v[124:127], v[10:13]
	v_mfma_f32_16x16x32_bf16 v[14:17], v[112:115], v[128:131], v[14:17]
	v_mfma_f32_16x16x32_bf16 v[10:13], v[120:123], v[128:131], v[10:13]
	s_setprio 0
	s_barrier
	s_add_u32 s94, s68, 0x80000
	s_addc_u32 s95, s69, 0
	s_add_i32 s96, s92, s72
	v_lshl_add_u64 v[102:103], s[94:95], 0, v[84:85]
	s_mov_b32 m0, s96
	s_nop 0
	global_load_lds_dwordx4 v[102:103], off
	v_lshl_add_u64 v[102:103], s[94:95], 0, v[86:87]
	s_add_i32 m0, s96, 0x2000
	s_nop 0
	global_load_lds_dwordx4 v[102:103], off
	s_waitcnt vmcnt(6)
	s_barrier
	s_setprio 1
	v_mfma_f32_16x16x32_bf16 v[6:9], v[156:159], v[124:127], v[6:9]
	v_mfma_f32_16x16x32_bf16 v[2:5], v[164:167], v[124:127], v[2:5]
	v_mfma_f32_16x16x32_bf16 v[6:9], v[160:163], v[128:131], v[6:9]
	v_mfma_f32_16x16x32_bf16 v[2:5], v[168:171], v[128:131], v[2:5]
	s_setprio 0
	s_add_i32 s94, 0, 0x18000
	v_add_u32_e32 v111, s94, v106
	s_barrier
	ds_read_b128 v[102:105], v111
	ds_read_b128 v[112:115], v111 offset:1024
	ds_read_b128 v[116:119], v111 offset:2048
	ds_read_b128 v[120:123], v111 offset:3072
	s_add_u32 s70, s70, 0x80000
	s_addc_u32 s71, s71, 0
	s_mov_b32 m0, s74
	v_lshl_add_u64 v[156:157], s[70:71], 0, v[84:85]
	ds_read_b128 v[124:127], v109 offset:32768
	ds_read_b128 v[128:131], v109 offset:33792
	ds_read_b128 v[132:135], v109 offset:34816
	ds_read_b128 v[136:139], v109 offset:35840
	ds_read_b128 v[140:143], v109 offset:36864
	ds_read_b128 v[144:147], v109 offset:37888
	ds_read_b128 v[148:151], v109 offset:38912
	ds_read_b128 v[152:155], v109 offset:39936
	global_load_lds_dwordx4 v[156:157], off
	v_lshl_add_u64 v[156:157], s[70:71], 0, v[86:87]
	s_mov_b32 m0, s75
	s_nop 0
	global_load_lds_dwordx4 v[156:157], off
	s_waitcnt lgkmcnt(8)
	s_barrier
	s_waitcnt lgkmcnt(0)
	s_setprio 1
	s_waitcnt lgkmcnt(0)
	v_mfma_f32_16x16x32_bf16 v[80:83], v[102:105], v[124:127], v[80:83]
	v_mfma_f32_16x16x32_bf16 v[76:79], v[116:119], v[124:127], v[76:79]
	v_mfma_f32_16x16x32_bf16 v[64:67], v[102:105], v[132:135], v[64:67]
	v_mfma_f32_16x16x32_bf16 v[60:63], v[116:119], v[132:135], v[60:63]
	v_mfma_f32_16x16x32_bf16 v[48:51], v[102:105], v[140:143], v[48:51]
	v_mfma_f32_16x16x32_bf16 v[44:47], v[116:119], v[140:143], v[44:47]
	v_mfma_f32_16x16x32_bf16 v[30:33], v[102:105], v[148:151], v[30:33]
	v_mfma_f32_16x16x32_bf16 v[26:29], v[116:119], v[148:151], v[26:29]
	v_mfma_f32_16x16x32_bf16 v[80:83], v[112:115], v[128:131], v[80:83]
	v_mfma_f32_16x16x32_bf16 v[76:79], v[120:123], v[128:131], v[76:79]
	v_mfma_f32_16x16x32_bf16 v[64:67], v[112:115], v[136:139], v[64:67]
	v_mfma_f32_16x16x32_bf16 v[60:63], v[120:123], v[136:139], v[60:63]
	v_mfma_f32_16x16x32_bf16 v[48:51], v[112:115], v[144:147], v[48:51]
	v_mfma_f32_16x16x32_bf16 v[44:47], v[120:123], v[144:147], v[44:47]
	v_mfma_f32_16x16x32_bf16 v[30:33], v[112:115], v[152:155], v[30:33]
	v_mfma_f32_16x16x32_bf16 v[26:29], v[120:123], v[152:155], v[26:29]
	s_setprio 0
	s_barrier
	s_add_i32 s70, 0, 0x1c000
	s_add_i32 s71, s94, s72
	v_add_u32_e32 v111, s70, v106
	v_lshl_add_u64 v[172:173], v[172:173], 0, s[18:19]
	s_mov_b32 m0, s71
	ds_read_b128 v[156:159], v111
	ds_read_b128 v[160:163], v111 offset:1024
	ds_read_b128 v[164:167], v111 offset:2048
	ds_read_b128 v[168:171], v111 offset:3072
	global_load_lds_dwordx4 v[172:173], off
	v_lshl_add_u64 v[172:173], v[174:175], 0, s[18:19]
	s_add_i32 m0, s71, 0x2000
	s_nop 0
	global_load_lds_dwordx4 v[172:173], off
	s_barrier
	s_waitcnt lgkmcnt(0)
	s_setprio 1
	s_waitcnt lgkmcnt(0)
	v_mfma_f32_16x16x32_bf16 v[72:75], v[156:159], v[124:127], v[72:75]
	v_mfma_f32_16x16x32_bf16 v[68:71], v[164:167], v[124:127], v[68:71]
	v_mfma_f32_16x16x32_bf16 v[56:59], v[156:159], v[132:135], v[56:59]
	v_mfma_f32_16x16x32_bf16 v[52:55], v[164:167], v[132:135], v[52:55]
	v_mfma_f32_16x16x32_bf16 v[40:43], v[156:159], v[140:143], v[40:43]
	v_mfma_f32_16x16x32_bf16 v[36:39], v[164:167], v[140:143], v[36:39]
	v_mfma_f32_16x16x32_bf16 v[22:25], v[156:159], v[148:151], v[22:25]
	v_mfma_f32_16x16x32_bf16 v[18:21], v[164:167], v[148:151], v[18:21]
	v_mfma_f32_16x16x32_bf16 v[72:75], v[160:163], v[128:131], v[72:75]
	v_mfma_f32_16x16x32_bf16 v[68:71], v[168:171], v[128:131], v[68:71]
	v_mfma_f32_16x16x32_bf16 v[56:59], v[160:163], v[136:139], v[56:59]
	v_mfma_f32_16x16x32_bf16 v[52:55], v[168:171], v[136:139], v[52:55]
	v_mfma_f32_16x16x32_bf16 v[40:43], v[160:163], v[144:147], v[40:43]
	v_mfma_f32_16x16x32_bf16 v[36:39], v[168:171], v[144:147], v[36:39]
	v_mfma_f32_16x16x32_bf16 v[22:25], v[160:163], v[152:155], v[22:25]
	v_mfma_f32_16x16x32_bf16 v[18:21], v[168:171], v[152:155], v[18:21]
	s_setprio 0
	s_mov_b32 m0, s87
	v_lshl_add_u64 v[132:133], v[176:177], 0, s[18:19]
	s_barrier
	ds_read_b128 v[124:127], v109 offset:49152
	ds_read_b128 v[128:131], v109 offset:50176
	global_load_lds_dwordx4 v[132:133], off
	v_lshl_add_u64 v[132:133], v[178:179], 0, s[18:19]
	s_mov_b32 m0, s90
	s_nop 0
	global_load_lds_dwordx4 v[132:133], off
	s_barrier
	s_waitcnt lgkmcnt(0)
	s_setprio 1
	s_waitcnt lgkmcnt(0)
	v_mfma_f32_16x16x32_bf16 v[14:17], v[102:105], v[124:127], v[14:17]
	v_mfma_f32_16x16x32_bf16 v[10:13], v[116:119], v[124:127], v[10:13]
	v_mfma_f32_16x16x32_bf16 v[14:17], v[112:115], v[128:131], v[14:17]
	v_mfma_f32_16x16x32_bf16 v[10:13], v[120:123], v[128:131], v[10:13]
	s_setprio 0
	s_barrier
	s_add_u32 s68, s68, 0x80080
	s_addc_u32 s69, s69, 0
	s_add_i32 s70, s70, s72
	v_lshl_add_u64 v[102:103], s[68:69], 0, v[84:85]
	s_mov_b32 m0, s70
	s_nop 0
	global_load_lds_dwordx4 v[102:103], off
	v_lshl_add_u64 v[102:103], s[68:69], 0, v[86:87]
	s_add_i32 m0, s70, 0x2000
	s_nop 0
	global_load_lds_dwordx4 v[102:103], off
	s_waitcnt vmcnt(6)
	s_barrier
	s_setprio 1
	v_mfma_f32_16x16x32_bf16 v[6:9], v[156:159], v[124:127], v[6:9]
	v_mfma_f32_16x16x32_bf16 v[2:5], v[164:167], v[124:127], v[2:5]
	v_mfma_f32_16x16x32_bf16 v[6:9], v[160:163], v[128:131], v[6:9]
	v_mfma_f32_16x16x32_bf16 v[2:5], v[168:171], v[128:131], v[2:5]
	s_setprio 0
	s_add_i32 s93, s93, 2
	s_add_u32 s52, s52, 0x100
	s_addc_u32 s53, s53, 0
	s_add_u32 s29, s29, 0x100
	s_addc_u32 s31, s31, 0
	s_cmp_gt_u32 s93, 13
	s_barrier
	s_cbranch_scc0 .LBB0_205
	v_lshl_or_b32 v102, s16, 8, v107
	v_ashrrev_i32_e32 v103, 31, v102
	s_cmp_lg_u32 s20, 0
	s_cbranch_scc1 .Lada_nobias
	v_lshl_add_u64 v[216:217], v[102:103], 2, s[54:55]
	global_load_dwordx4 v[200:203], v[216:217], off
	global_load_dwordx4 v[204:207], v[216:217], off offset:64
	global_load_dwordx4 v[208:211], v[216:217], off offset:512
	global_load_dwordx4 v[212:215], v[216:217], off offset:576
	s_waitcnt vmcnt(0)
.Lada_nobias:
	s_and_saveexec_b64 s[52:53], s[6:7]
	s_cbranch_execnz .LBB0_211
	s_or_b64 exec, exec, s[52:53]
	s_and_saveexec_b64 s[52:53], s[8:9]
	s_cbranch_execnz .LBB0_220

.LBB0_211:
	s_cmp_eq_u32 s20, 0
	s_cselect_b64 s[68:69], -1, 0
	s_cmp_lg_u32 s20, 0
	s_cbranch_scc1 .LBB0_213
	v_pk_add_f32 v[82:83], v[82:83], v[202:203]
	v_pk_add_f32 v[80:81], v[80:81], v[200:201]
.LBB0_213:
	v_lshl_add_u64 v[104:105], v[102:103], 2, v[88:89]
	global_atomic_add_f32 v[104:105], v80, off
	global_atomic_add_f32 v[104:105], v81, off offset:4
	global_atomic_add_f32 v[104:105], v82, off offset:8
	global_atomic_add_f32 v[104:105], v83, off offset:12
	v_cndmask_b32_e64 v80, 0, 1, s[68:69]
	v_cmp_ne_u32_e64 s[16:17], 1, v80
	s_andn2_b64 vcc, exec, s[68:69]
	s_cbranch_vccnz .LBB0_215
	v_pk_add_f32 v[78:79], v[78:79], v[206:207]
	v_pk_add_f32 v[76:77], v[76:77], v[204:205]
.LBB0_215:
	global_atomic_add_f32 v[104:105], v76, off offset:64
	global_atomic_add_f32 v[104:105], v77, off offset:68
	global_atomic_add_f32 v[104:105], v78, off offset:72
	global_atomic_add_f32 v[104:105], v79, off offset:76
	s_and_b64 vcc, exec, s[16:17]
	s_cbranch_vccnz .LBB0_217
	v_pk_add_f32 v[74:75], v[74:75], v[210:211]
	v_pk_add_f32 v[72:73], v[72:73], v[208:209]
.LBB0_217:
	global_atomic_add_f32 v[104:105], v72, off offset:512
	global_atomic_add_f32 v[104:105], v73, off offset:516
	global_atomic_add_f32 v[104:105], v74, off offset:520
	global_atomic_add_f32 v[104:105], v75, off offset:524
	s_and_b64 vcc, exec, s[16:17]
	s_cbranch_vccnz .LBB0_219
	v_pk_add_f32 v[70:71], v[70:71], v[214:215]
	v_pk_add_f32 v[68:69], v[68:69], v[212:213]

.LBB0_220:
	s_cmp_eq_u32 s20, 0
	s_cselect_b64 s[68:69], -1, 0
	s_cmp_lg_u32 s20, 0
	s_cbranch_scc1 .LBB0_222
	v_pk_add_f32 v[66:67], v[66:67], v[202:203]
	v_pk_add_f32 v[64:65], v[64:65], v[200:201]
.LBB0_222:
	v_lshl_add_u64 v[68:69], v[102:103], 2, v[90:91]
	global_atomic_add_f32 v[68:69], v64, off
	global_atomic_add_f32 v[68:69], v65, off offset:4
	global_atomic_add_f32 v[68:69], v66, off offset:8
	global_atomic_add_f32 v[68:69], v67, off offset:12
	v_cndmask_b32_e64 v64, 0, 1, s[68:69]
	v_cmp_ne_u32_e64 s[16:17], 1, v64
	s_andn2_b64 vcc, exec, s[68:69]
	s_cbranch_vccnz .LBB0_224
	v_pk_add_f32 v[62:63], v[62:63], v[206:207]
	v_pk_add_f32 v[60:61], v[60:61], v[204:205]
.LBB0_224:
	global_atomic_add_f32 v[68:69], v60, off offset:64
	global_atomic_add_f32 v[68:69], v61, off offset:68
	global_atomic_add_f32 v[68:69], v62, off offset:72
	global_atomic_add_f32 v[68:69], v63, off offset:76
	s_and_b64 vcc, exec, s[16:17]
	s_cbranch_vccnz .LBB0_226
	v_pk_add_f32 v[58:59], v[58:59], v[210:211]
	v_pk_add_f32 v[56:57], v[56:57], v[208:209]
.LBB0_226:
	global_atomic_add_f32 v[68:69], v56, off offset:512
	global_atomic_add_f32 v[68:69], v57, off offset:516
	global_atomic_add_f32 v[68:69], v58, off offset:520
	global_atomic_add_f32 v[68:69], v59, off offset:524
	s_and_b64 vcc, exec, s[16:17]
	s_cbranch_vccnz .LBB0_228
	v_pk_add_f32 v[54:55], v[54:55], v[214:215]
	v_pk_add_f32 v[52:53], v[52:53], v[212:213]

.LBB0_229:
	s_cmp_eq_u32 s20, 0
	s_cselect_b64 s[68:69], -1, 0
	s_cmp_lg_u32 s20, 0
	s_cbranch_scc1 .LBB0_231
	v_pk_add_f32 v[50:51], v[50:51], v[202:203]
	v_pk_add_f32 v[48:49], v[48:49], v[200:201]
.LBB0_231:
	v_lshl_add_u64 v[52:53], v[102:103], 2, v[92:93]
	global_atomic_add_f32 v[52:53], v48, off
	global_atomic_add_f32 v[52:53], v49, off offset:4
	global_atomic_add_f32 v[52:53], v50, off offset:8
	global_atomic_add_f32 v[52:53], v51, off offset:12
	v_cndmask_b32_e64 v48, 0, 1, s[68:69]
	v_cmp_ne_u32_e64 s[16:17], 1, v48
	s_andn2_b64 vcc, exec, s[68:69]
	s_cbranch_vccnz .LBB0_233
	v_pk_add_f32 v[46:47], v[46:47], v[206:207]
	v_pk_add_f32 v[44:45], v[44:45], v[204:205]
.LBB0_233:
	global_atomic_add_f32 v[52:53], v44, off offset:64
	global_atomic_add_f32 v[52:53], v45, off offset:68
	global_atomic_add_f32 v[52:53], v46, off offset:72
	global_atomic_add_f32 v[52:53], v47, off offset:76
	s_and_b64 vcc, exec, s[16:17]
	s_cbranch_vccnz .LBB0_235
	v_pk_add_f32 v[42:43], v[42:43], v[210:211]
	v_pk_add_f32 v[40:41], v[40:41], v[208:209]
.LBB0_235:
	global_atomic_add_f32 v[52:53], v40, off offset:512
	global_atomic_add_f32 v[52:53], v41, off offset:516
	global_atomic_add_f32 v[52:53], v42, off offset:520
	global_atomic_add_f32 v[52:53], v43, off offset:524
	s_and_b64 vcc, exec, s[16:17]
	s_cbranch_vccnz .LBB0_237
	v_pk_add_f32 v[38:39], v[38:39], v[214:215]
	v_pk_add_f32 v[36:37], v[36:37], v[212:213]

.LBB0_238:
	s_cmp_eq_u32 s20, 0
	s_cselect_b64 s[68:69], -1, 0
	s_cmp_lg_u32 s20, 0
	s_cbranch_scc1 .LBB0_240
	v_pk_add_f32 v[32:33], v[32:33], v[202:203]
	v_pk_add_f32 v[30:31], v[30:31], v[200:201]
.LBB0_240:
	v_lshl_add_u64 v[36:37], v[102:103], 2, v[94:95]
	global_atomic_add_f32 v[36:37], v30, off
	global_atomic_add_f32 v[36:37], v31, off offset:4
	global_atomic_add_f32 v[36:37], v32, off offset:8
	global_atomic_add_f32 v[36:37], v33, off offset:12
	v_cndmask_b32_e64 v30, 0, 1, s[68:69]
	v_cmp_ne_u32_e64 s[16:17], 1, v30
	s_andn2_b64 vcc, exec, s[68:69]
	s_cbranch_vccnz .LBB0_242
	v_pk_add_f32 v[28:29], v[28:29], v[206:207]
	v_pk_add_f32 v[26:27], v[26:27], v[204:205]
.LBB0_242:
	global_atomic_add_f32 v[36:37], v26, off offset:64
	global_atomic_add_f32 v[36:37], v27, off offset:68
	global_atomic_add_f32 v[36:37], v28, off offset:72
	global_atomic_add_f32 v[36:37], v29, off offset:76
	s_and_b64 vcc, exec, s[16:17]
	s_cbranch_vccnz .LBB0_244
	v_pk_add_f32 v[24:25], v[24:25], v[210:211]
	v_pk_add_f32 v[22:23], v[22:23], v[208:209]
.LBB0_244:
	global_atomic_add_f32 v[36:37], v22, off offset:512
	global_atomic_add_f32 v[36:37], v23, off offset:516
	global_atomic_add_f32 v[36:37], v24, off offset:520
	global_atomic_add_f32 v[36:37], v25, off offset:524
	s_and_b64 vcc, exec, s[16:17]
	s_cbranch_vccnz .LBB0_246
	v_pk_add_f32 v[20:21], v[20:21], v[214:215]
	v_pk_add_f32 v[18:19], v[18:19], v[212:213]

.LBB0_247:
	s_cmp_eq_u32 s20, 0
	s_cselect_b64 s[68:69], -1, 0
	s_cmp_lg_u32 s20, 0
	s_cbranch_scc1 .LBB0_249
	v_pk_add_f32 v[16:17], v[16:17], v[202:203]
	v_pk_add_f32 v[14:15], v[14:15], v[200:201]
.LBB0_249:
	v_lshl_add_u64 v[18:19], v[102:103], 2, v[96:97]
	global_atomic_add_f32 v[18:19], v14, off
	global_atomic_add_f32 v[18:19], v15, off offset:4
	global_atomic_add_f32 v[18:19], v16, off offset:8
	global_atomic_add_f32 v[18:19], v17, off offset:12
	v_cndmask_b32_e64 v14, 0, 1, s[68:69]
	v_cmp_ne_u32_e64 s[16:17], 1, v14
	s_andn2_b64 vcc, exec, s[68:69]
	s_cbranch_vccnz .LBB0_251
	v_pk_add_f32 v[12:13], v[12:13], v[206:207]
	v_pk_add_f32 v[10:11], v[10:11], v[204:205]
.LBB0_251:
	v_or_b32_e32 v14, 16, v102
	v_ashrrev_i32_e32 v15, 31, v14
	v_lshl_add_u64 v[14:15], v[14:15], 2, v[96:97]
	global_atomic_add_f32 v[14:15], v10, off
	global_atomic_add_f32 v[14:15], v11, off offset:4
	global_atomic_add_f32 v[14:15], v12, off offset:8
	global_atomic_add_f32 v[14:15], v13, off offset:12
	s_and_b64 vcc, exec, s[16:17]
	s_cbranch_vccnz .LBB0_253
	v_pk_add_f32 v[8:9], v[8:9], v[210:211]
	v_pk_add_f32 v[6:7], v[6:7], v[208:209]
.LBB0_253:
	v_or_b32_e32 v10, 0x80, v102
	v_ashrrev_i32_e32 v11, 31, v10
	v_lshl_add_u64 v[10:11], v[10:11], 2, v[96:97]
	global_atomic_add_f32 v[10:11], v6, off
	global_atomic_add_f32 v[10:11], v7, off offset:4
	global_atomic_add_f32 v[10:11], v8, off offset:8
	global_atomic_add_f32 v[10:11], v9, off offset:12
	s_and_b64 vcc, exec, s[16:17]
	s_cbranch_vccnz .LBB0_200
	v_pk_add_f32 v[4:5], v[4:5], v[214:215]
	v_pk_add_f32 v[2:3], v[2:3], v[212:213]
	s_branch .LBB0_200
